# cooperative attention: next tile's K DMAs issued right after the last K read (barrier C), V DMAs after the last V read: each DMA batch lands under a compute half-tile
# speedup vs baseline: 1.0950x; 1.0145x over previous
; __device__ __forceinline__ void nat_phase(const Params& p, float* ldsf, int wave0, int nwaves) {
;     ...
;         for (int qt = 0; qt < 4; ++qt) {
;             const int c0 = qt * 16, cs0 = (qt == 0) ? 0 : (qt == 1 ? 8 : (qt == 2 ? 24 : 32));
;             const int c = c0 + l15, csq = min(max(c - 8, 0), 48);
;             const bf16x8 bq0 = *(const bf16x8*)(Qb + (size_t)c * RW + lq * 8), bq1 = *(const bf16x8*)(Qb + (size_t)c * RW + 32 + lq * 8);
.Lmy_nat_cqt:
	s_lshl_b32 s82, s16, 4
	s_add_i32 s83, s82, -8
	s_max_i32 s83, s83, 0
	s_min_i32 s83, s83, 32
	s_lshl_b32 s84, s82, 11
	s_add_u32 s84, s84, s76
	buffer_load_dwordx4 v[192:195], v224, s[68:71], s84 offen
	buffer_load_dwordx4 v[196:199], v224, s[68:71], s84 offen offset:64
	s_barrier
	s_cmp_lt_u32 s1, 4
	s_cbranch_scc0 .Lmy_nat_p1v
	s_cmp_eq_u32 s16, 0
	s_cbranch_scc0 .Lmy_nat_p1kw
	s_lshl_b32 s91, s83, 11
	s_add_u32 s91, s91, s77
	s_lshr_b32 s85, s1, 1
	s_lshl_b32 s85, s85, 13
	s_add_u32 s91, s91, s85
	s_and_b32 s85, s1, 1
	s_lshl_b32 s85, s85, 6
	s_add_u32 s91, s91, s85
	s_mov_b32 s93, 0x20000
	s_lshl_b32 s86, s1, 10
	s_mov_b32 m0, s86
	s_nop 0
	buffer_load_dwordx4 v34, s[68:71], s91 offen lds
	s_add_u32 m0, m0, 0x1000
	s_add_u32 s91, s91, s93
	buffer_load_dwordx4 v34, s[68:71], s91 offen lds
	s_add_u32 m0, m0, 0x1000
	s_add_u32 s91, s91, s93
	buffer_load_dwordx4 v34, s[68:71], s91 offen lds
	s_add_u32 m0, m0, 0x1000
	s_add_u32 s91, s91, s93
	buffer_load_dwordx4 v34, s[68:71], s91 offen lds
	s_add_u32 m0, m0, 0x1000
	s_add_u32 s91, s91, s93
	buffer_load_dwordx4 v34, s[68:71], s91 offen lds
	s_add_u32 m0, m0, 0x1000
	s_add_u32 s91, s91, s93
	buffer_load_dwordx4 v34, s[68:71], s91 offen lds
	s_add_u32 m0, m0, 0x1000
	s_add_u32 s91, s91, s93
	buffer_load_dwordx4 v34, s[68:71], s91 offen lds
	s_add_u32 m0, m0, 0x1000
	s_add_u32 s91, s91, s93
	buffer_load_dwordx4 v34, s[68:71], s91 offen lds
	s_add_u32 m0, m0, 0x1000
	s_add_u32 s91, s91, s93
	buffer_load_dwordx4 v34, s[68:71], s91 offen lds
	s_add_u32 m0, m0, 0x1000
	s_add_u32 s91, s91, s93
	buffer_load_dwordx4 v34, s[68:71], s91 offen lds
	s_add_u32 m0, m0, 0x1000
	s_add_u32 s91, s91, s93
	buffer_load_dwordx4 v34, s[68:71], s91 offen lds
	s_add_u32 m0, m0, 0x1000
	s_add_u32 s91, s91, s93
	buffer_load_dwordx4 v34, s[68:71], s91 offen lds
	s_add_u32 m0, m0, 0x1000
	s_add_u32 s91, s91, s93
	buffer_load_dwordx4 v34, s[68:71], s91 offen lds
	s_add_u32 m0, m0, 0x1000
	s_add_u32 s91, s91, s93
	buffer_load_dwordx4 v34, s[68:71], s91 offen lds
	s_add_u32 m0, m0, 0x1000
	s_add_u32 s91, s91, s93
	buffer_load_dwordx4 v34, s[68:71], s91 offen lds
	s_waitcnt vmcnt(0)
	s_branch .Lmy_nat_p1j
.Lmy_nat_p1kw:
	s_waitcnt vmcnt(6)
	s_branch .Lmy_nat_p1j
.Lmy_nat_p1v:
	s_lshl_b32 s91, s83, 1
	s_add_u32 s91, s91, s78
	s_and_b32 s85, s1, 3
	s_lshl_b32 s85, s85, 19
	s_add_u32 s91, s91, s85
	s_movk_i32 s93, 0x80
	s_and_b32 s86, s1, 3
	s_lshl_b32 s86, s86, 10
	s_add_u32 s86, s86, 0xf000
	s_mov_b32 m0, s86
	s_nop 0
	buffer_load_dwordx4 v34, s[68:71], s91 offen lds
	s_add_u32 m0, m0, 0x1000
	s_add_u32 s91, s91, s93
	buffer_load_dwordx4 v34, s[68:71], s91 offen lds
	s_add_u32 m0, m0, 0x1000
	s_add_u32 s91, s91, s93
	buffer_load_dwordx4 v34, s[68:71], s91 offen lds
	s_add_u32 m0, m0, 0x1000
	s_add_u32 s91, s91, s93
	buffer_load_dwordx4 v34, s[68:71], s91 offen lds
	s_add_u32 m0, m0, 0x1000
	s_add_u32 s91, s91, s93
	buffer_load_dwordx4 v34, s[68:71], s91 offen lds
	s_add_u32 m0, m0, 0x1000
	s_add_u32 s91, s91, s93
	buffer_load_dwordx4 v34, s[68:71], s91 offen lds
	s_add_u32 m0, m0, 0x1000
	s_add_u32 s91, s91, s93
	buffer_load_dwordx4 v34, s[68:71], s91 offen lds
	s_add_u32 m0, m0, 0x1000
	s_add_u32 s91, s91, s93
	buffer_load_dwordx4 v34, s[68:71], s91 offen lds
	s_add_u32 m0, m0, 0x1000
	s_add_u32 s91, s91, s93
	buffer_load_dwordx4 v34, s[68:71], s91 offen lds
	s_add_u32 m0, m0, 0x1000
	s_add_u32 s91, s91, s93
	buffer_load_dwordx4 v34, s[68:71], s91 offen lds
	s_add_u32 m0, m0, 0x1000
	s_add_u32 s91, s91, s93
	buffer_load_dwordx4 v34, s[68:71], s91 offen lds
	s_add_u32 m0, m0, 0x1000
	s_add_u32 s91, s91, s93
	buffer_load_dwordx4 v34, s[68:71], s91 offen lds
	s_add_u32 m0, m0, 0x1000
	s_add_u32 s91, s91, s93
	buffer_load_dwordx4 v34, s[68:71], s91 offen lds
	s_add_u32 m0, m0, 0x1000
	s_add_u32 s91, s91, s93
	buffer_load_dwordx4 v34, s[68:71], s91 offen lds
	s_add_u32 m0, m0, 0x1000
	s_add_u32 s91, s91, s93
	buffer_load_dwordx4 v34, s[68:71], s91 offen lds
; __device__ __forceinline__ void nat_phase(const Params& p, float* ldsf, int wave0, int nwaves) {
;     ...
;         { const float* rpb = p.rpb + h * 465 + (rs - r + 7) * 31;
; #pragma unroll
;           for (int q = 0; q < 4; ++q) { const int e = lane + q * 64; if (e < 248) tb[e] = rpb[e]; } }
;     ...
;                     for (int j = 0; j < 4; ++j) { const int kc = cs0 + lq * 8 + hf * 4 + j; const bool valid = (kc >= csq) && (kc < csq + 16); const int bc = valid ? (kc - c + 15) : 0;
;                         const float s = valid ? sc[i][hf][j] * 0.125f + tb[i * 31 + bc] : -1e30f; sc[i][hf][j] = s; mx = fmaxf(mx, s); }
.Lmy_nat_p1j:
	s_barrier
	v_add_u32_e32 v241, s82, v237
	v_add_u32_e32 v242, -8, v241
	v_med3_i32 v242, v242, 0, 48
	v_lshl_add_u32 v251, v238, 3, s83
	v_sub_u32_e32 v243, v251, v242
	v_sub_u32_e32 v244, v251, v241
	v_lshl_add_u32 v244, v244, 2, s3
	v_mov_b32_e32 v245, 0x1e800
	v_add_u32_e32 v246, 0, v243
	v_cmp_gt_u32_e32 vcc, 16, v246
	v_add_u32_e32 v247, 60, v244
	s_nop 0
	v_cndmask_b32_e32 v229, v245, v247, vcc
	v_add_u32_e32 v246, 1, v243
	v_cmp_gt_u32_e32 vcc, 16, v246
	v_add_u32_e32 v247, 64, v244
	s_nop 0
	v_cndmask_b32_e32 v230, v245, v247, vcc
	v_add_u32_e32 v246, 2, v243
	v_cmp_gt_u32_e32 vcc, 16, v246
	v_add_u32_e32 v247, 68, v244
	s_nop 0
	v_cndmask_b32_e32 v231, v245, v247, vcc
	v_add_u32_e32 v246, 3, v243
	v_cmp_gt_u32_e32 vcc, 16, v246
	v_add_u32_e32 v247, 72, v244
	s_nop 0
	v_cndmask_b32_e32 v232, v245, v247, vcc
	v_add_u32_e32 v246, 4, v243
	v_cmp_gt_u32_e32 vcc, 16, v246
	v_add_u32_e32 v247, 76, v244
	s_nop 0
	v_cndmask_b32_e32 v233, v245, v247, vcc
	v_add_u32_e32 v246, 5, v243
	v_cmp_gt_u32_e32 vcc, 16, v246
	v_add_u32_e32 v247, 80, v244
	s_nop 0
	v_cndmask_b32_e32 v234, v245, v247, vcc
	v_add_u32_e32 v246, 6, v243
	v_cmp_gt_u32_e32 vcc, 16, v246
	v_add_u32_e32 v247, 84, v244
	s_nop 0
	v_cndmask_b32_e32 v235, v245, v247, vcc
	v_add_u32_e32 v246, 7, v243
	v_cmp_gt_u32_e32 vcc, 16, v246
	v_add_u32_e32 v247, 88, v244
	s_nop 0
	v_cndmask_b32_e32 v236, v245, v247, vcc
	ds_read_b32 v128, v229 offset:0
	ds_read_b32 v129, v230 offset:0
	ds_read_b32 v130, v231 offset:0
	ds_read_b32 v131, v232 offset:0
	ds_read_b32 v132, v233 offset:0
	ds_read_b32 v133, v234 offset:0
	ds_read_b32 v134, v235 offset:0
	ds_read_b32 v135, v236 offset:0
	ds_read_b32 v136, v229 offset:124
	ds_read_b32 v137, v230 offset:124
	ds_read_b32 v138, v231 offset:124
	ds_read_b32 v139, v232 offset:124
	ds_read_b32 v140, v233 offset:124
	ds_read_b32 v141, v234 offset:124
	ds_read_b32 v142, v235 offset:124
	ds_read_b32 v143, v236 offset:124
	ds_read_b32 v144, v229 offset:248
	ds_read_b32 v145, v230 offset:248
	ds_read_b32 v146, v231 offset:248
	ds_read_b32 v147, v232 offset:248
	ds_read_b32 v148, v233 offset:248
	ds_read_b32 v149, v234 offset:248
	ds_read_b32 v150, v235 offset:248
	ds_read_b32 v151, v236 offset:248
	ds_read_b32 v152, v229 offset:372
	ds_read_b32 v153, v230 offset:372
	ds_read_b32 v154, v231 offset:372
	ds_read_b32 v155, v232 offset:372
	ds_read_b32 v156, v233 offset:372
	ds_read_b32 v157, v234 offset:372
	ds_read_b32 v158, v235 offset:372
	ds_read_b32 v159, v236 offset:372
	ds_read_b32 v160, v229 offset:496
	ds_read_b32 v161, v230 offset:496
	ds_read_b32 v162, v231 offset:496
	ds_read_b32 v163, v232 offset:496
	ds_read_b32 v164, v233 offset:496
	ds_read_b32 v165, v234 offset:496
	ds_read_b32 v166, v235 offset:496
	ds_read_b32 v167, v236 offset:496
	ds_read_b32 v168, v229 offset:620
	ds_read_b32 v169, v230 offset:620
	ds_read_b32 v170, v231 offset:620
	ds_read_b32 v171, v232 offset:620
	ds_read_b32 v172, v233 offset:620
	ds_read_b32 v173, v234 offset:620
	ds_read_b32 v174, v235 offset:620
	ds_read_b32 v175, v236 offset:620
	ds_read_b32 v176, v229 offset:744
	ds_read_b32 v177, v230 offset:744
	ds_read_b32 v178, v231 offset:744
	ds_read_b32 v179, v232 offset:744
	ds_read_b32 v180, v233 offset:744
	ds_read_b32 v181, v234 offset:744
	ds_read_b32 v182, v235 offset:744
	ds_read_b32 v183, v236 offset:744
	ds_read_b32 v184, v229 offset:868
	ds_read_b32 v185, v230 offset:868
	ds_read_b32 v186, v231 offset:868
	ds_read_b32 v187, v232 offset:868
	ds_read_b32 v188, v233 offset:868
	ds_read_b32 v189, v234 offset:868
	ds_read_b32 v190, v235 offset:868
	ds_read_b32 v191, v236 offset:868
	s_cmp_lt_u32 s1, 4
	s_cbranch_scc0 .Lmy_nat_p2v
	s_waitcnt vmcnt(0)
	s_branch .Lmy_nat_p2j

; __device__ __forceinline__ void nat_phase(const Params& p, float* ldsf, int wave0, int nwaves) {
;     ...
;             f32x4 sc[8][2];
; #pragma unroll
;             for (int i = 0; i < 8; ++i)
; #pragma unroll
;                 for (int hf = 0; hf < 2; ++hf) { const u16* kp = Kb + (size_t)(i * 64 + cs0 + (l15 >> 2) * 8 + hf * 4 + (l15 & 3)) * RW + lq * 8;
;                     const bf16x8 a0 = *(const bf16x8*)kp, a1 = *(const bf16x8*)(kp + 32); f32x4 z = {0.f, 0.f, 0.f, 0.f};
;                     z = __builtin_amdgcn_mfma_f32_16x16x32_bf16(a0, bq0, z, 0, 0, 0); z = __builtin_amdgcn_mfma_f32_16x16x32_bf16(a1, bq1, z, 0, 0, 0); sc[i][hf] = z; }
;             float mx = -1e30f;
; #pragma unroll
;             for (int i = 0; i < 8; ++i)
; #pragma unroll
;                 for (int hf = 0; hf < 2; ++hf)
; #pragma unroll
;                     for (int j = 0; j < 4; ++j) { const int kc = cs0 + lq * 8 + hf * 4 + j; const bool valid = (kc >= csq) && (kc < csq + 16); const int bc = valid ? (kc - c + 15) : 0;
;                         const float s = valid ? sc[i][hf][j] * 0.125f + tb[i * 31 + bc] : -1e30f; sc[i][hf][j] = s; mx = fmaxf(mx, s); }
;             mx = fmaxf(mx, __shfl_xor(mx, 16)); mx = fmaxf(mx, __shfl_xor(mx, 32));
;     ...
;             for (int mt = 0; mt < 4; ++mt) { const int ch = h * 64 + mt * 16 + lq * 4; const u32x2 gw = *(const u32x2*)(Gn + tok * RW + ch);
.Lmy_nat_p2j:
	s_waitcnt lgkmcnt(0)
	ds_read_b128 v[0:3], v32 offset:0
	ds_read_b128 v[4:7], v32 offset:1024
	ds_read_b128 v[8:11], v32 offset:2048
	ds_read_b128 v[12:15], v32 offset:3072
	ds_read_b128 v[16:19], v32 offset:4096
	ds_read_b128 v[20:23], v32 offset:5120
	ds_read_b128 v[24:27], v32 offset:6144
	ds_read_b128 v[28:31], v32 offset:7168
	s_waitcnt lgkmcnt(7)
	v_mfma_f32_16x16x32_bf16 v[128:131], v[0:3], v[192:195], v[128:131]
	ds_read_b128 v[0:3], v32 offset:8192
	s_waitcnt lgkmcnt(7)
	v_mfma_f32_16x16x32_bf16 v[128:131], v[4:7], v[196:199], v[128:131]
	ds_read_b128 v[4:7], v32 offset:9216
	s_waitcnt lgkmcnt(7)
	v_mfma_f32_16x16x32_bf16 v[132:135], v[8:11], v[192:195], v[132:135]
	ds_read_b128 v[8:11], v32 offset:10240
	s_waitcnt lgkmcnt(7)
	v_mfma_f32_16x16x32_bf16 v[132:135], v[12:15], v[196:199], v[132:135]
	ds_read_b128 v[12:15], v32 offset:11264
	s_waitcnt lgkmcnt(7)
	v_mfma_f32_16x16x32_bf16 v[136:139], v[16:19], v[192:195], v[136:139]
	ds_read_b128 v[16:19], v32 offset:12288
	s_waitcnt lgkmcnt(7)
	v_mfma_f32_16x16x32_bf16 v[136:139], v[20:23], v[196:199], v[136:139]
	ds_read_b128 v[20:23], v32 offset:13312
	s_waitcnt lgkmcnt(7)
	v_mfma_f32_16x16x32_bf16 v[140:143], v[24:27], v[192:195], v[140:143]
	ds_read_b128 v[24:27], v32 offset:14336
	s_waitcnt lgkmcnt(7)
	v_mfma_f32_16x16x32_bf16 v[140:143], v[28:31], v[196:199], v[140:143]
	ds_read_b128 v[28:31], v32 offset:15360
	s_waitcnt lgkmcnt(7)
	v_mfma_f32_16x16x32_bf16 v[144:147], v[0:3], v[192:195], v[144:147]
	ds_read_b128 v[0:3], v32 offset:16384
	s_waitcnt lgkmcnt(7)
	v_mfma_f32_16x16x32_bf16 v[144:147], v[4:7], v[196:199], v[144:147]
	ds_read_b128 v[4:7], v32 offset:17408
	s_waitcnt lgkmcnt(7)
	v_mfma_f32_16x16x32_bf16 v[148:151], v[8:11], v[192:195], v[148:151]
	ds_read_b128 v[8:11], v32 offset:18432
	s_waitcnt lgkmcnt(7)
	v_mfma_f32_16x16x32_bf16 v[148:151], v[12:15], v[196:199], v[148:151]
	ds_read_b128 v[12:15], v32 offset:19456
	s_waitcnt lgkmcnt(7)
	v_mfma_f32_16x16x32_bf16 v[152:155], v[16:19], v[192:195], v[152:155]
	ds_read_b128 v[16:19], v32 offset:20480
	s_waitcnt lgkmcnt(7)
	v_mfma_f32_16x16x32_bf16 v[152:155], v[20:23], v[196:199], v[152:155]
	ds_read_b128 v[20:23], v32 offset:21504
	s_waitcnt lgkmcnt(7)
	v_mfma_f32_16x16x32_bf16 v[156:159], v[24:27], v[192:195], v[156:159]
	ds_read_b128 v[24:27], v32 offset:22528
	s_waitcnt lgkmcnt(7)
	v_mfma_f32_16x16x32_bf16 v[156:159], v[28:31], v[196:199], v[156:159]
	ds_read_b128 v[28:31], v32 offset:23552
	s_waitcnt lgkmcnt(7)
	v_mfma_f32_16x16x32_bf16 v[160:163], v[0:3], v[192:195], v[160:163]
	ds_read_b128 v[0:3], v32 offset:24576
	s_waitcnt lgkmcnt(7)
	v_mfma_f32_16x16x32_bf16 v[160:163], v[4:7], v[196:199], v[160:163]
	ds_read_b128 v[4:7], v32 offset:25600
	s_waitcnt lgkmcnt(7)
	v_mfma_f32_16x16x32_bf16 v[164:167], v[8:11], v[192:195], v[164:167]
	ds_read_b128 v[8:11], v32 offset:26624
	s_waitcnt lgkmcnt(7)
	v_mfma_f32_16x16x32_bf16 v[164:167], v[12:15], v[196:199], v[164:167]
	ds_read_b128 v[12:15], v32 offset:27648
	s_waitcnt lgkmcnt(7)
	v_mfma_f32_16x16x32_bf16 v[168:171], v[16:19], v[192:195], v[168:171]
	ds_read_b128 v[16:19], v32 offset:28672
	s_waitcnt lgkmcnt(7)
	v_mfma_f32_16x16x32_bf16 v[168:171], v[20:23], v[196:199], v[168:171]
	ds_read_b128 v[20:23], v32 offset:29696
	s_waitcnt lgkmcnt(7)
	v_mfma_f32_16x16x32_bf16 v[172:175], v[24:27], v[192:195], v[172:175]
	ds_read_b128 v[24:27], v32 offset:30720
	s_waitcnt lgkmcnt(7)
	v_mfma_f32_16x16x32_bf16 v[172:175], v[28:31], v[196:199], v[172:175]
	ds_read_b128 v[28:31], v32 offset:31744
	s_waitcnt lgkmcnt(7)
	v_mfma_f32_16x16x32_bf16 v[176:179], v[0:3], v[192:195], v[176:179]
	s_waitcnt lgkmcnt(6)
	v_mfma_f32_16x16x32_bf16 v[176:179], v[4:7], v[196:199], v[176:179]
	s_waitcnt lgkmcnt(5)
	v_mfma_f32_16x16x32_bf16 v[180:183], v[8:11], v[192:195], v[180:183]
	s_waitcnt lgkmcnt(4)
	v_mfma_f32_16x16x32_bf16 v[180:183], v[12:15], v[196:199], v[180:183]
	s_waitcnt lgkmcnt(3)
	v_mfma_f32_16x16x32_bf16 v[184:187], v[16:19], v[192:195], v[184:187]
	s_waitcnt lgkmcnt(2)
	v_mfma_f32_16x16x32_bf16 v[184:187], v[20:23], v[196:199], v[184:187]
	s_waitcnt lgkmcnt(1)
	v_mfma_f32_16x16x32_bf16 v[188:191], v[24:27], v[192:195], v[188:191]
	s_waitcnt lgkmcnt(0)
	v_mfma_f32_16x16x32_bf16 v[188:191], v[28:31], v[196:199], v[188:191]
	s_lshl_b32 s84, s82, 11
	s_add_u32 s84, s84, s79
	buffer_load_dwordx2 v[216:217], v227, s[68:71], s84 offen offset:0
	buffer_load_dwordx2 v[218:219], v227, s[68:71], s84 offen offset:32
	buffer_load_dwordx2 v[220:221], v227, s[68:71], s84 offen offset:64
	buffer_load_dwordx2 v[222:223], v227, s[68:71], s84 offen offset:96
	v_max3_f32 v239, v128, v129, v130
	v_max3_f32 v239, v239, v131, v132
	v_max3_f32 v239, v239, v133, v134
	v_max3_f32 v239, v239, v135, v136
	v_max3_f32 v239, v239, v137, v138
	v_max3_f32 v239, v239, v139, v140
	v_max3_f32 v239, v239, v141, v142
	v_max3_f32 v239, v239, v143, v144
	v_max3_f32 v239, v239, v145, v146
	v_max3_f32 v239, v239, v147, v148
	v_max3_f32 v239, v239, v149, v150
	v_max3_f32 v239, v239, v151, v152
	v_max3_f32 v239, v239, v153, v154
	v_max3_f32 v239, v239, v155, v156
	v_max3_f32 v239, v239, v157, v158
	v_max3_f32 v239, v239, v159, v160
	v_max3_f32 v239, v239, v161, v162
	v_max3_f32 v239, v239, v163, v164
	v_max3_f32 v239, v239, v165, v166
	v_max3_f32 v239, v239, v167, v168
	v_max3_f32 v239, v239, v169, v170
	v_max3_f32 v239, v239, v171, v172
	v_max3_f32 v239, v239, v173, v174
	v_max3_f32 v239, v239, v175, v176
	v_max3_f32 v239, v239, v177, v178
	v_max3_f32 v239, v239, v179, v180
	v_max3_f32 v239, v239, v181, v182
	v_max3_f32 v239, v239, v183, v184
	v_max3_f32 v239, v239, v185, v186
	v_max3_f32 v239, v239, v187, v188
	v_max3_f32 v239, v239, v189, v190
	v_max_f32_e32 v239, v239, v191
	ds_bpermute_b32 v242, v248, v239
	s_waitcnt lgkmcnt(0)
; __device__ __forceinline__ void nat_phase(const Params& p, float* ldsf, int wave0, int nwaves) {
;     ...
;             mx = fmaxf(mx, __shfl_xor(mx, 16)); mx = fmaxf(mx, __shfl_xor(mx, 32));
;             float sum = 0.f;
; #pragma unroll
;             for (int i = 0; i < 8; ++i)
; #pragma unroll
;                 for (int hf = 0; hf < 2; ++hf)
; #pragma unroll
;                     for (int j = 0; j < 4; ++j) { const float e = __expf(sc[i][hf][j] - mx); sc[i][hf][j] = e; sum += e; }
;             sum += __shfl_xor(sum, 16); sum += __shfl_xor(sum, 32);
	v_max_f32_e32 v239, v239, v242
	ds_bpermute_b32 v242, v249, v239
	s_waitcnt lgkmcnt(0)
	v_max_f32_e32 v239, v239, v242
	v_mul_f32_e64 v242, -v239, v252
	v_mov_b32_e32 v243, v242
	v_pk_fma_f32 v[128:129], v[128:129], v[252:253], v[242:243]
	v_pk_fma_f32 v[130:131], v[130:131], v[252:253], v[242:243]
	v_pk_fma_f32 v[132:133], v[132:133], v[252:253], v[242:243]
	v_pk_fma_f32 v[134:135], v[134:135], v[252:253], v[242:243]
	v_pk_fma_f32 v[136:137], v[136:137], v[252:253], v[242:243]
	v_pk_fma_f32 v[138:139], v[138:139], v[252:253], v[242:243]
	v_pk_fma_f32 v[140:141], v[140:141], v[252:253], v[242:243]
	v_pk_fma_f32 v[142:143], v[142:143], v[252:253], v[242:243]
	v_pk_fma_f32 v[144:145], v[144:145], v[252:253], v[242:243]
	v_pk_fma_f32 v[146:147], v[146:147], v[252:253], v[242:243]
	v_pk_fma_f32 v[148:149], v[148:149], v[252:253], v[242:243]
	v_pk_fma_f32 v[150:151], v[150:151], v[252:253], v[242:243]
	v_pk_fma_f32 v[152:153], v[152:153], v[252:253], v[242:243]
	v_pk_fma_f32 v[154:155], v[154:155], v[252:253], v[242:243]
	v_pk_fma_f32 v[156:157], v[156:157], v[252:253], v[242:243]
	v_pk_fma_f32 v[158:159], v[158:159], v[252:253], v[242:243]
	v_pk_fma_f32 v[160:161], v[160:161], v[252:253], v[242:243]
	v_pk_fma_f32 v[162:163], v[162:163], v[252:253], v[242:243]
	v_pk_fma_f32 v[164:165], v[164:165], v[252:253], v[242:243]
	v_pk_fma_f32 v[166:167], v[166:167], v[252:253], v[242:243]
	v_pk_fma_f32 v[168:169], v[168:169], v[252:253], v[242:243]
	v_pk_fma_f32 v[170:171], v[170:171], v[252:253], v[242:243]
	v_pk_fma_f32 v[172:173], v[172:173], v[252:253], v[242:243]
	v_pk_fma_f32 v[174:175], v[174:175], v[252:253], v[242:243]
	v_pk_fma_f32 v[176:177], v[176:177], v[252:253], v[242:243]
	v_pk_fma_f32 v[178:179], v[178:179], v[252:253], v[242:243]
	v_pk_fma_f32 v[180:181], v[180:181], v[252:253], v[242:243]
	v_pk_fma_f32 v[182:183], v[182:183], v[252:253], v[242:243]
	v_pk_fma_f32 v[184:185], v[184:185], v[252:253], v[242:243]
	v_pk_fma_f32 v[186:187], v[186:187], v[252:253], v[242:243]
	v_pk_fma_f32 v[188:189], v[188:189], v[252:253], v[242:243]
	v_pk_fma_f32 v[190:191], v[190:191], v[252:253], v[242:243]
	v_exp_f32_e32 v128, v128
	v_exp_f32_e32 v129, v129
	v_exp_f32_e32 v130, v130
	v_exp_f32_e32 v131, v131
	v_exp_f32_e32 v132, v132
	v_exp_f32_e32 v133, v133
	v_exp_f32_e32 v134, v134
	v_exp_f32_e32 v135, v135
	v_exp_f32_e32 v136, v136
	v_exp_f32_e32 v137, v137
	v_exp_f32_e32 v138, v138
	v_exp_f32_e32 v139, v139
	v_exp_f32_e32 v140, v140
	v_exp_f32_e32 v141, v141
	v_exp_f32_e32 v142, v142
	v_exp_f32_e32 v143, v143
	v_exp_f32_e32 v144, v144
	v_exp_f32_e32 v145, v145
	v_exp_f32_e32 v146, v146
	v_exp_f32_e32 v147, v147
	v_exp_f32_e32 v148, v148
	v_exp_f32_e32 v149, v149
	v_exp_f32_e32 v150, v150
	v_exp_f32_e32 v151, v151
	v_exp_f32_e32 v152, v152
	v_exp_f32_e32 v153, v153
	v_exp_f32_e32 v154, v154
	v_exp_f32_e32 v155, v155
	v_exp_f32_e32 v156, v156
	v_exp_f32_e32 v157, v157
	v_exp_f32_e32 v158, v158
	v_exp_f32_e32 v159, v159
	v_exp_f32_e32 v160, v160
	v_exp_f32_e32 v161, v161
	v_exp_f32_e32 v162, v162
	v_exp_f32_e32 v163, v163
	v_exp_f32_e32 v164, v164
	v_exp_f32_e32 v165, v165
	v_exp_f32_e32 v166, v166
	v_exp_f32_e32 v167, v167
	v_exp_f32_e32 v168, v168
	v_exp_f32_e32 v169, v169
	v_exp_f32_e32 v170, v170
	v_exp_f32_e32 v171, v171
	v_exp_f32_e32 v172, v172
	v_exp_f32_e32 v173, v173
	v_exp_f32_e32 v174, v174
	v_exp_f32_e32 v175, v175
	v_exp_f32_e32 v176, v176
	v_exp_f32_e32 v177, v177
	v_exp_f32_e32 v178, v178
	v_exp_f32_e32 v179, v179
	v_exp_f32_e32 v180, v180
	v_exp_f32_e32 v181, v181
	v_exp_f32_e32 v182, v182
	v_exp_f32_e32 v183, v183
	v_exp_f32_e32 v184, v184
	v_exp_f32_e32 v185, v185
	v_exp_f32_e32 v186, v186
	v_exp_f32_e32 v187, v187
	v_exp_f32_e32 v188, v188
	v_exp_f32_e32 v189, v189
	v_exp_f32_e32 v190, v190
	v_exp_f32_e32 v191, v191
	s_nop 0
	v_pk_add_f32 v[244:245], v[128:129], v[130:131]
	v_pk_add_f32 v[246:247], v[132:133], v[134:135]
	v_pk_add_f32 v[244:245], v[244:245], v[136:137]
	v_pk_add_f32 v[246:247], v[246:247], v[138:139]
	v_pk_add_f32 v[244:245], v[244:245], v[140:141]
	v_pk_add_f32 v[246:247], v[246:247], v[142:143]
	v_pk_add_f32 v[244:245], v[244:245], v[144:145]
	v_pk_add_f32 v[246:247], v[246:247], v[146:147]
	v_pk_add_f32 v[244:245], v[244:245], v[148:149]
	v_pk_add_f32 v[246:247], v[246:247], v[150:151]
	v_pk_add_f32 v[244:245], v[244:245], v[152:153]
	v_pk_add_f32 v[246:247], v[246:247], v[154:155]
	v_pk_add_f32 v[244:245], v[244:245], v[156:157]
	v_pk_add_f32 v[246:247], v[246:247], v[158:159]
	v_pk_add_f32 v[244:245], v[244:245], v[160:161]
	v_pk_add_f32 v[246:247], v[246:247], v[162:163]
	v_pk_add_f32 v[244:245], v[244:245], v[164:165]
	v_pk_add_f32 v[246:247], v[246:247], v[166:167]
	v_pk_add_f32 v[244:245], v[244:245], v[168:169]
	v_pk_add_f32 v[246:247], v[246:247], v[170:171]
	v_pk_add_f32 v[244:245], v[244:245], v[172:173]
	v_pk_add_f32 v[246:247], v[246:247], v[174:175]
	v_pk_add_f32 v[244:245], v[244:245], v[176:177]
	v_pk_add_f32 v[246:247], v[246:247], v[178:179]
	v_pk_add_f32 v[244:245], v[244:245], v[180:181]
	v_pk_add_f32 v[246:247], v[246:247], v[182:183]
	v_pk_add_f32 v[244:245], v[244:245], v[184:185]
	v_pk_add_f32 v[246:247], v[246:247], v[186:187]
	v_pk_add_f32 v[244:245], v[244:245], v[188:189]
	v_pk_add_f32 v[246:247], v[246:247], v[190:191]
	v_pk_add_f32 v[244:245], v[244:245], v[246:247]
	v_add_f32_e32 v240, v244, v245
	ds_bpermute_b32 v242, v248, v240
	s_waitcnt lgkmcnt(0)
	v_add_f32_e32 v240, v240, v242
	ds_bpermute_b32 v242, v249, v240
	s_waitcnt lgkmcnt(0)
; __device__ __forceinline__ unsigned cvt_pk_bf16(float lo, float hi) { unsigned r; asm volatile("v_cvt_pk_bf16_f32 %0, %1, %2" : "=v"(r) : "v"(lo), "v"(hi)); return r; }
; __device__ __forceinline__ void nat_phase(const Params& p, float* ldsf, int wave0, int nwaves) {
;     ...
;             const float inv = 1.0f / sum;
;             f32x4 o[4];
; #pragma unroll
;             for (int mt = 0; mt < 4; ++mt) o[mt] = (f32x4){0.f, 0.f, 0.f, 0.f};
; #pragma unroll
;             for (int i = 0; i < 8; ++i) {
;                 u32x4 pw; pw.x = cvt_pk_bf16(sc[i][0][0] * inv, sc[i][0][1] * inv); pw.y = cvt_pk_bf16(sc[i][0][2] * inv, sc[i][0][3] * inv);
;                 pw.z = cvt_pk_bf16(sc[i][1][0] * inv, sc[i][1][1] * inv); pw.w = cvt_pk_bf16(sc[i][1][2] * inv, sc[i][1][3] * inv);
;                 const bf16x8 bp = __builtin_bit_cast(bf16x8, pw);
	v_add_f32_e32 v240, v240, v242
	v_rcp_f32_e32 v242, v240
	s_nop 0
	v_mov_b32_e32 v243, v242
	v_pk_mul_f32 v[128:129], v[128:129], v[242:243]
	v_pk_mul_f32 v[130:131], v[130:131], v[242:243]
	v_pk_mul_f32 v[132:133], v[132:133], v[242:243]
	v_pk_mul_f32 v[134:135], v[134:135], v[242:243]
	v_pk_mul_f32 v[136:137], v[136:137], v[242:243]
	v_pk_mul_f32 v[138:139], v[138:139], v[242:243]
	v_pk_mul_f32 v[140:141], v[140:141], v[242:243]
	v_pk_mul_f32 v[142:143], v[142:143], v[242:243]
	v_pk_mul_f32 v[144:145], v[144:145], v[242:243]
	v_pk_mul_f32 v[146:147], v[146:147], v[242:243]
	v_pk_mul_f32 v[148:149], v[148:149], v[242:243]
	v_pk_mul_f32 v[150:151], v[150:151], v[242:243]
	v_pk_mul_f32 v[152:153], v[152:153], v[242:243]
	v_pk_mul_f32 v[154:155], v[154:155], v[242:243]
	v_pk_mul_f32 v[156:157], v[156:157], v[242:243]
	v_pk_mul_f32 v[158:159], v[158:159], v[242:243]
	v_pk_mul_f32 v[160:161], v[160:161], v[242:243]
	v_pk_mul_f32 v[162:163], v[162:163], v[242:243]
	v_pk_mul_f32 v[164:165], v[164:165], v[242:243]
	v_pk_mul_f32 v[166:167], v[166:167], v[242:243]
	v_pk_mul_f32 v[168:169], v[168:169], v[242:243]
	v_pk_mul_f32 v[170:171], v[170:171], v[242:243]
	v_pk_mul_f32 v[172:173], v[172:173], v[242:243]
	v_pk_mul_f32 v[174:175], v[174:175], v[242:243]
	v_pk_mul_f32 v[176:177], v[176:177], v[242:243]
	v_pk_mul_f32 v[178:179], v[178:179], v[242:243]
	v_pk_mul_f32 v[180:181], v[180:181], v[242:243]
	v_pk_mul_f32 v[182:183], v[182:183], v[242:243]
	v_pk_mul_f32 v[184:185], v[184:185], v[242:243]
	v_pk_mul_f32 v[186:187], v[186:187], v[242:243]
	v_pk_mul_f32 v[188:189], v[188:189], v[242:243]
	v_pk_mul_f32 v[190:191], v[190:191], v[242:243]
	v_cvt_pk_bf16_f32 v128, v128, v129
	v_cvt_pk_bf16_f32 v129, v130, v131
	v_cvt_pk_bf16_f32 v130, v132, v133
	v_cvt_pk_bf16_f32 v131, v134, v135
	v_cvt_pk_bf16_f32 v136, v136, v137
	v_cvt_pk_bf16_f32 v137, v138, v139
	v_cvt_pk_bf16_f32 v138, v140, v141
	v_cvt_pk_bf16_f32 v139, v142, v143
	v_cvt_pk_bf16_f32 v144, v144, v145
	v_cvt_pk_bf16_f32 v145, v146, v147
	v_cvt_pk_bf16_f32 v146, v148, v149
	v_cvt_pk_bf16_f32 v147, v150, v151
	v_cvt_pk_bf16_f32 v152, v152, v153
	v_cvt_pk_bf16_f32 v153, v154, v155
	v_cvt_pk_bf16_f32 v154, v156, v157
	v_cvt_pk_bf16_f32 v155, v158, v159
	v_cvt_pk_bf16_f32 v160, v160, v161
	v_cvt_pk_bf16_f32 v161, v162, v163
	v_cvt_pk_bf16_f32 v162, v164, v165
	v_cvt_pk_bf16_f32 v163, v166, v167
	v_cvt_pk_bf16_f32 v168, v168, v169
	v_cvt_pk_bf16_f32 v169, v170, v171
	v_cvt_pk_bf16_f32 v170, v172, v173
	v_cvt_pk_bf16_f32 v171, v174, v175
	v_cvt_pk_bf16_f32 v176, v176, v177
	v_cvt_pk_bf16_f32 v177, v178, v179
	v_cvt_pk_bf16_f32 v178, v180, v181
	v_cvt_pk_bf16_f32 v179, v182, v183
	v_cvt_pk_bf16_f32 v184, v184, v185
	v_cvt_pk_bf16_f32 v185, v186, v187
	v_cvt_pk_bf16_f32 v186, v188, v189
	v_cvt_pk_bf16_f32 v187, v190, v191
	s_cmp_lt_u32 s1, 4
	s_cbranch_scc1 .Lmy_nat_p3j
	s_waitcnt vmcnt(4)
.Lmy_nat_p3j:
	s_barrier
	s_cmp_lt_u32 s1, 4
	s_cbranch_scc0 .Lmy_nat_p4j
	s_cmp_lt_u32 s16, 3
	s_cbranch_scc0 .Lmy_nat_p4j
	s_add_i32 s87, s82, 8
	s_min_i32 s87, s87, 32
	s_lshl_b32 s91, s87, 11
	s_add_u32 s91, s91, s77
	s_lshr_b32 s85, s1, 1
	s_lshl_b32 s85, s85, 13
	s_add_u32 s91, s91, s85
	s_and_b32 s85, s1, 1
	s_lshl_b32 s85, s85, 6
	s_add_u32 s91, s91, s85
	s_mov_b32 s93, 0x20000
	s_lshl_b32 s86, s1, 10
	s_mov_b32 m0, s86
	s_nop 0
	buffer_load_dwordx4 v34, s[68:71], s91 offen lds
	s_add_u32 m0, m0, 0x1000
	s_add_u32 s91, s91, s93
	buffer_load_dwordx4 v34, s[68:71], s91 offen lds
	s_add_u32 m0, m0, 0x1000
	s_add_u32 s91, s91, s93
	buffer_load_dwordx4 v34, s[68:71], s91 offen lds
	s_add_u32 m0, m0, 0x1000
	s_add_u32 s91, s91, s93
	buffer_load_dwordx4 v34, s[68:71], s91 offen lds
	s_add_u32 m0, m0, 0x1000
	s_add_u32 s91, s91, s93
	buffer_load_dwordx4 v34, s[68:71], s91 offen lds
	s_add_u32 m0, m0, 0x1000
	s_add_u32 s91, s91, s93
	buffer_load_dwordx4 v34, s[68:71], s91 offen lds
	s_add_u32 m0, m0, 0x1000
	s_add_u32 s91, s91, s93
	buffer_load_dwordx4 v34, s[68:71], s91 offen lds
	s_add_u32 m0, m0, 0x1000
	s_add_u32 s91, s91, s93
	buffer_load_dwordx4 v34, s[68:71], s91 offen lds
	s_add_u32 m0, m0, 0x1000
	s_add_u32 s91, s91, s93
	buffer_load_dwordx4 v34, s[68:71], s91 offen lds
	s_add_u32 m0, m0, 0x1000
	s_add_u32 s91, s91, s93
	buffer_load_dwordx4 v34, s[68:71], s91 offen lds
	s_add_u32 m0, m0, 0x1000
	s_add_u32 s91, s91, s93
	buffer_load_dwordx4 v34, s[68:71], s91 offen lds
	s_add_u32 m0, m0, 0x1000
	s_add_u32 s91, s91, s93
	buffer_load_dwordx4 v34, s[68:71], s91 offen lds
	s_add_u32 m0, m0, 0x1000
	s_add_u32 s91, s91, s93
	buffer_load_dwordx4 v34, s[68:71], s91 offen lds
	s_add_u32 m0, m0, 0x1000
	s_add_u32 s91, s91, s93
	buffer_load_dwordx4 v34, s[68:71], s91 offen lds
	s_add_u32 m0, m0, 0x1000
	s_add_u32 s91, s91, s93
	buffer_load_dwordx4 v34, s[68:71], s91 offen lds
; __device__ __forceinline__ unsigned cvt_pk_bf16(float lo, float hi) { unsigned r; asm volatile("v_cvt_pk_bf16_f32 %0, %1, %2" : "=v"(r) : "v"(lo), "v"(hi)); return r; }
; __device__ __forceinline__ void nat_phase(const Params& p, float* ldsf, int wave0, int nwaves) {
;     ...
;             for (int i = 0; i < 8; ++i) {
;                 u32x4 pw; pw.x = cvt_pk_bf16(sc[i][0][0] * inv, sc[i][0][1] * inv); pw.y = cvt_pk_bf16(sc[i][0][2] * inv, sc[i][0][3] * inv);
;                 pw.z = cvt_pk_bf16(sc[i][1][0] * inv, sc[i][1][1] * inv); pw.w = cvt_pk_bf16(sc[i][1][2] * inv, sc[i][1][3] * inv);
;                 const bf16x8 bp = __builtin_bit_cast(bf16x8, pw);
; #pragma unroll
;                 for (int mt = 0; mt < 4; ++mt) { const u16* vp = Vb + (size_t)(mt * 16 + l15) * SEQ + i * 64 + cs0 + lq * 8;
;                     o[mt] = __builtin_amdgcn_mfma_f32_16x16x32_bf16(*(const bf16x8*)vp, bp, o[mt], 0, 0, 0); }
;             }
.Lmy_nat_p4j:
	ds_read_b128 v[0:3], v33 offset:0
	ds_read_b128 v[4:7], v33 offset:1024
	ds_read_b128 v[8:11], v33 offset:2048
	ds_read_b128 v[12:15], v33 offset:3072
	ds_read_b128 v[16:19], v33 offset:4096
	ds_read_b128 v[20:23], v33 offset:5120
	ds_read_b128 v[24:27], v33 offset:6144
	ds_read_b128 v[28:31], v33 offset:7168
	s_waitcnt lgkmcnt(7)
	v_mfma_f32_16x16x32_bf16 v[200:203], v[0:3], v[128:131], 0
	ds_read_b128 v[0:3], v33 offset:8192
	s_waitcnt lgkmcnt(7)
	v_mfma_f32_16x16x32_bf16 v[204:207], v[4:7], v[128:131], 0
	ds_read_b128 v[4:7], v33 offset:9216
	s_waitcnt lgkmcnt(7)
	v_mfma_f32_16x16x32_bf16 v[208:211], v[8:11], v[128:131], 0
	ds_read_b128 v[8:11], v33 offset:10240
	s_waitcnt lgkmcnt(7)
	v_mfma_f32_16x16x32_bf16 v[212:215], v[12:15], v[128:131], 0
	ds_read_b128 v[12:15], v33 offset:11264
	s_waitcnt lgkmcnt(7)
	v_mfma_f32_16x16x32_bf16 v[200:203], v[16:19], v[136:139], v[200:203]
	ds_read_b128 v[16:19], v33 offset:12288
	s_waitcnt lgkmcnt(7)
	v_mfma_f32_16x16x32_bf16 v[204:207], v[20:23], v[136:139], v[204:207]
	ds_read_b128 v[20:23], v33 offset:13312
	s_waitcnt lgkmcnt(7)
	v_mfma_f32_16x16x32_bf16 v[208:211], v[24:27], v[136:139], v[208:211]
	ds_read_b128 v[24:27], v33 offset:14336
	s_waitcnt lgkmcnt(7)
	v_mfma_f32_16x16x32_bf16 v[212:215], v[28:31], v[136:139], v[212:215]
	ds_read_b128 v[28:31], v33 offset:15360
	s_waitcnt lgkmcnt(7)
	v_mfma_f32_16x16x32_bf16 v[200:203], v[0:3], v[144:147], v[200:203]
	ds_read_b128 v[0:3], v33 offset:16384
	s_waitcnt lgkmcnt(7)
	v_mfma_f32_16x16x32_bf16 v[204:207], v[4:7], v[144:147], v[204:207]
	ds_read_b128 v[4:7], v33 offset:17408
	s_waitcnt lgkmcnt(7)
	v_mfma_f32_16x16x32_bf16 v[208:211], v[8:11], v[144:147], v[208:211]
	ds_read_b128 v[8:11], v33 offset:18432
	s_waitcnt lgkmcnt(7)
	v_mfma_f32_16x16x32_bf16 v[212:215], v[12:15], v[144:147], v[212:215]
	ds_read_b128 v[12:15], v33 offset:19456
	s_waitcnt lgkmcnt(7)
	v_mfma_f32_16x16x32_bf16 v[200:203], v[16:19], v[152:155], v[200:203]
	ds_read_b128 v[16:19], v33 offset:20480
	s_waitcnt lgkmcnt(7)
	v_mfma_f32_16x16x32_bf16 v[204:207], v[20:23], v[152:155], v[204:207]
	ds_read_b128 v[20:23], v33 offset:21504
	s_waitcnt lgkmcnt(7)
	v_mfma_f32_16x16x32_bf16 v[208:211], v[24:27], v[152:155], v[208:211]
	ds_read_b128 v[24:27], v33 offset:22528
	s_waitcnt lgkmcnt(7)
	v_mfma_f32_16x16x32_bf16 v[212:215], v[28:31], v[152:155], v[212:215]
	ds_read_b128 v[28:31], v33 offset:23552
	s_waitcnt lgkmcnt(7)
	v_mfma_f32_16x16x32_bf16 v[200:203], v[0:3], v[160:163], v[200:203]
	ds_read_b128 v[0:3], v33 offset:24576
	s_waitcnt lgkmcnt(7)
	v_mfma_f32_16x16x32_bf16 v[204:207], v[4:7], v[160:163], v[204:207]
	ds_read_b128 v[4:7], v33 offset:25600
	s_waitcnt lgkmcnt(7)
	v_mfma_f32_16x16x32_bf16 v[208:211], v[8:11], v[160:163], v[208:211]
	ds_read_b128 v[8:11], v33 offset:26624
	s_waitcnt lgkmcnt(7)
	v_mfma_f32_16x16x32_bf16 v[212:215], v[12:15], v[160:163], v[212:215]
	ds_read_b128 v[12:15], v33 offset:27648
	s_waitcnt lgkmcnt(7)
	v_mfma_f32_16x16x32_bf16 v[200:203], v[16:19], v[168:171], v[200:203]
	ds_read_b128 v[16:19], v33 offset:28672
	s_waitcnt lgkmcnt(7)
	v_mfma_f32_16x16x32_bf16 v[204:207], v[20:23], v[168:171], v[204:207]
	ds_read_b128 v[20:23], v33 offset:29696
	s_waitcnt lgkmcnt(7)
	v_mfma_f32_16x16x32_bf16 v[208:211], v[24:27], v[168:171], v[208:211]
	ds_read_b128 v[24:27], v33 offset:30720
	s_waitcnt lgkmcnt(7)
	v_mfma_f32_16x16x32_bf16 v[212:215], v[28:31], v[168:171], v[212:215]
	ds_read_b128 v[28:31], v33 offset:31744
	s_waitcnt lgkmcnt(7)
	v_mfma_f32_16x16x32_bf16 v[200:203], v[0:3], v[176:179], v[200:203]
	s_waitcnt lgkmcnt(6)
	v_mfma_f32_16x16x32_bf16 v[204:207], v[4:7], v[176:179], v[204:207]
	s_waitcnt lgkmcnt(5)
	v_mfma_f32_16x16x32_bf16 v[208:211], v[8:11], v[176:179], v[208:211]
	s_waitcnt lgkmcnt(4)
	v_mfma_f32_16x16x32_bf16 v[212:215], v[12:15], v[176:179], v[212:215]
	s_waitcnt lgkmcnt(3)
	v_mfma_f32_16x16x32_bf16 v[200:203], v[16:19], v[184:187], v[200:203]
	s_waitcnt lgkmcnt(2)
	v_mfma_f32_16x16x32_bf16 v[204:207], v[20:23], v[184:187], v[204:207]
	s_waitcnt lgkmcnt(1)
	v_mfma_f32_16x16x32_bf16 v[208:211], v[24:27], v[184:187], v[208:211]
	s_waitcnt lgkmcnt(0)
	v_mfma_f32_16x16x32_bf16 v[212:215], v[28:31], v[184:187], v[212:215]
	s_cmp_lt_u32 s1, 4
	s_cbranch_scc0 .Lmy_nat_p5z
	s_cmp_lt_u32 s16, 3
	s_cbranch_scc0 .Lmy_nat_p5z
	s_waitcnt vmcnt(15)
	s_branch .Lmy_nat_p5j

; __device__ __forceinline__ float bflo(unsigned w) { return __uint_as_float(w << 16); }
; __device__ __forceinline__ float bfhi(unsigned w) { return __uint_as_float(w & 0xffff0000u); }
; __device__ __forceinline__ unsigned cvt_pk_bf16(float lo, float hi) { unsigned r; asm volatile("v_cvt_pk_bf16_f32 %0, %1, %2" : "=v"(r) : "v"(lo), "v"(hi)); return r; }
; __device__ __forceinline__ float sigmoidf_(float x) { return __builtin_amdgcn_rcpf(1.0f + __expf(-x)); }
; __device__ __forceinline__ void nat_phase(const Params& p, float* ldsf, int wave0, int nwaves) {
;     ...
;         for (int qt = 0; qt < 4; ++qt) {
;     ...
;             const size_t tok = (size_t)(b * SEQ + r * 64 + c);
; #pragma unroll
;             for (int mt = 0; mt < 4; ++mt) { const int ch = h * 64 + mt * 16 + lq * 4; const u32x2 gw = *(const u32x2*)(Gn + tok * RW + ch);
;                 const float g0 = bflo(gw.x), g1 = bfhi(gw.x), g2 = bflo(gw.y), g3 = bfhi(gw.y);
;                 u32x2 w; w.x = cvt_pk_bf16(o[mt][0] * g0 * sigmoidf_(g0), o[mt][1] * g1 * sigmoidf_(g1)); w.y = cvt_pk_bf16(o[mt][2] * g2 * sigmoidf_(g2), o[mt][3] * g3 * sigmoidf_(g3));
;                 *(u32x2*)(MIX + tok * DM + 1024 + ch) = w; }
.Lmy_nat_p5j:
	s_lshl_b32 s84, s82, 12
	s_add_u32 s84, s84, s80
	v_lshlrev_b32_e32 v132, 16, v216
	v_and_b32_e32 v133, 0xffff0000, v216
	v_lshlrev_b32_e32 v134, 16, v217
	v_and_b32_e32 v135, 0xffff0000, v217
	v_lshlrev_b32_e32 v140, 16, v218
	v_and_b32_e32 v141, 0xffff0000, v218
	v_lshlrev_b32_e32 v142, 16, v219
	v_and_b32_e32 v143, 0xffff0000, v219
	v_lshlrev_b32_e32 v148, 16, v220
	v_and_b32_e32 v149, 0xffff0000, v220
	v_lshlrev_b32_e32 v150, 16, v221
	v_and_b32_e32 v151, 0xffff0000, v221
	v_lshlrev_b32_e32 v156, 16, v222
	v_and_b32_e32 v157, 0xffff0000, v222
	v_lshlrev_b32_e32 v158, 16, v223
	v_and_b32_e32 v159, 0xffff0000, v223
	v_mul_f32_e32 v164, 0xbfb8aa3b, v132
	v_mul_f32_e32 v165, 0xbfb8aa3b, v133
	v_mul_f32_e32 v166, 0xbfb8aa3b, v134
	v_mul_f32_e32 v167, 0xbfb8aa3b, v135
	v_mul_f32_e32 v172, 0xbfb8aa3b, v140
	v_mul_f32_e32 v173, 0xbfb8aa3b, v141
	v_mul_f32_e32 v174, 0xbfb8aa3b, v142
	v_mul_f32_e32 v175, 0xbfb8aa3b, v143
	v_mul_f32_e32 v180, 0xbfb8aa3b, v148
	v_mul_f32_e32 v181, 0xbfb8aa3b, v149
	v_mul_f32_e32 v182, 0xbfb8aa3b, v150
	v_mul_f32_e32 v183, 0xbfb8aa3b, v151
	v_mul_f32_e32 v188, 0xbfb8aa3b, v156
	v_mul_f32_e32 v189, 0xbfb8aa3b, v157
	v_mul_f32_e32 v190, 0xbfb8aa3b, v158
	v_mul_f32_e32 v191, 0xbfb8aa3b, v159
	v_exp_f32_e32 v164, v164
	v_exp_f32_e32 v165, v165
	v_exp_f32_e32 v166, v166
	v_exp_f32_e32 v167, v167
	v_exp_f32_e32 v172, v172
	v_exp_f32_e32 v173, v173
	v_exp_f32_e32 v174, v174
	v_exp_f32_e32 v175, v175
	v_exp_f32_e32 v180, v180
	v_exp_f32_e32 v181, v181
	v_exp_f32_e32 v182, v182
	v_exp_f32_e32 v183, v183
	v_exp_f32_e32 v188, v188
	v_exp_f32_e32 v189, v189
	v_exp_f32_e32 v190, v190
	v_exp_f32_e32 v191, v191
	s_nop 0
	v_add_f32_e32 v164, 1.0, v164
	v_add_f32_e32 v165, 1.0, v165
	v_add_f32_e32 v166, 1.0, v166
	v_add_f32_e32 v167, 1.0, v167
	v_add_f32_e32 v172, 1.0, v172
	v_add_f32_e32 v173, 1.0, v173
	v_add_f32_e32 v174, 1.0, v174
	v_add_f32_e32 v175, 1.0, v175
	v_add_f32_e32 v180, 1.0, v180
	v_add_f32_e32 v181, 1.0, v181
	v_add_f32_e32 v182, 1.0, v182
	v_add_f32_e32 v183, 1.0, v183
	v_add_f32_e32 v188, 1.0, v188
	v_add_f32_e32 v189, 1.0, v189
	v_add_f32_e32 v190, 1.0, v190
	v_add_f32_e32 v191, 1.0, v191
	v_rcp_f32_e32 v164, v164
	v_rcp_f32_e32 v165, v165
	v_rcp_f32_e32 v166, v166
	v_rcp_f32_e32 v167, v167
	v_rcp_f32_e32 v172, v172
	v_rcp_f32_e32 v173, v173
	v_rcp_f32_e32 v174, v174
	v_rcp_f32_e32 v175, v175
	v_rcp_f32_e32 v180, v180
	v_rcp_f32_e32 v181, v181
	v_rcp_f32_e32 v182, v182
	v_rcp_f32_e32 v183, v183
	v_rcp_f32_e32 v188, v188
	v_rcp_f32_e32 v189, v189
	v_rcp_f32_e32 v190, v190
	v_rcp_f32_e32 v191, v191
	s_nop 0
	v_mul_f32_e32 v200, v200, v132
	v_mul_f32_e32 v201, v201, v133
	v_mul_f32_e32 v202, v202, v134
	v_mul_f32_e32 v203, v203, v135
	v_mul_f32_e32 v204, v204, v140
	v_mul_f32_e32 v205, v205, v141
	v_mul_f32_e32 v206, v206, v142
	v_mul_f32_e32 v207, v207, v143
	v_mul_f32_e32 v208, v208, v148
	v_mul_f32_e32 v209, v209, v149
	v_mul_f32_e32 v210, v210, v150
	v_mul_f32_e32 v211, v211, v151
	v_mul_f32_e32 v212, v212, v156
	v_mul_f32_e32 v213, v213, v157
	v_mul_f32_e32 v214, v214, v158
	v_mul_f32_e32 v215, v215, v159
	v_mul_f32_e32 v200, v200, v164
	v_mul_f32_e32 v201, v201, v165
	v_mul_f32_e32 v202, v202, v166
	v_mul_f32_e32 v203, v203, v167
	v_mul_f32_e32 v204, v204, v172
	v_mul_f32_e32 v205, v205, v173
	v_mul_f32_e32 v206, v206, v174
	v_mul_f32_e32 v207, v207, v175
	v_mul_f32_e32 v208, v208, v180
	v_mul_f32_e32 v209, v209, v181
	v_mul_f32_e32 v210, v210, v182
	v_mul_f32_e32 v211, v211, v183
	v_mul_f32_e32 v212, v212, v188
	v_mul_f32_e32 v213, v213, v189
	v_mul_f32_e32 v214, v214, v190
	v_mul_f32_e32 v215, v215, v191
	v_cvt_pk_bf16_f32 v200, v200, v201
	v_cvt_pk_bf16_f32 v201, v202, v203
	v_cvt_pk_bf16_f32 v204, v204, v205
	v_cvt_pk_bf16_f32 v205, v206, v207
	v_cvt_pk_bf16_f32 v208, v208, v209
	v_cvt_pk_bf16_f32 v209, v210, v211
	v_cvt_pk_bf16_f32 v212, v212, v213
	v_cvt_pk_bf16_f32 v213, v214, v215
	buffer_store_dwordx2 v[200:201], v228, s[64:67], s84 offen offset:0
	buffer_store_dwordx2 v[204:205], v228, s[64:67], s84 offen offset:32
	buffer_store_dwordx2 v[208:209], v228, s[64:67], s84 offen offset:64
	buffer_store_dwordx2 v[212:213], v228, s[64:67], s84 offen offset:96
	s_add_u32 s16, s16, 1
	s_cmp_lt_u32 s16, 4
	s_cbranch_scc1 .Lmy_nat_cqt
	s_add_u32 s88, s88, s94
	s_branch .Lmy_nat_unit
